# L0 out-proj GEMM: removed compiler vmcnt(0) at epilogue start and in tile prologues (residual loads overlap next-tile DMA landing; stores drain during first k-tile)
# speedup vs baseline: 1.0075x; 1.0075x over previous
; DEV int tid_l() { int t = threadIdx.x; asm volatile("" : "+v"(t)); return t; }
; DEV int stage_next(int s) { return (s == 2 * GS_STAGE) ? 0 : s + GS_STAGE; }
; DEV void gk_issue2(const GTile& t, int s0) {
;   const int tid = tid_l(), lane = tid & 63, wid = __builtin_amdgcn_readfirstlane(tid >> 6);
;   GK_SRC(t)
;   asm volatile("" ::: "memory");
;   GK_DMA(s0, 0);
;   GK_DMA(stage_next(s0), 1);
;   asm volatile("" ::: "memory");
; }
; DEV void epi_resid_f32(const f32x16 (&acc)[2][2], const float* base, float* out, int m0, int n0, int stg) {
;   const int tid = tid_l(), lane = tid & 63, wid = tid >> 6, wm = wid & 1, wn = wid >> 1, l32 = lane & 31, hi = lane >> 5;
;   unsigned char* wl = smem + stg + wid * 6144;
;   const size_t o0 = (size_t)(m0 + 64 * wm + (lane >> 3)) * DM + n0 + 64 * wn + (lane & 7) * 4;
;   f32x4 bb[2][2][4];
; #pragma unroll
;   for (int mb = 0; mb < 2; ++mb)
; #pragma unroll
;     for (int nb = 0; nb < 2; ++nb)
; #pragma unroll
;       for (int it = 0; it < 4; ++it) bb[mb][nb][it] = *(const f32x4*)(base + o0 + (size_t)(32 * mb + 8 * it) * DM + 32 * nb);
; #pragma unroll
;   for (int mb = 0; mb < 2; ++mb)
; #pragma unroll
;     for (int nb = 0; nb < 2; ++nb) {
; #pragma unroll
;       for (int rq = 0; rq < 4; ++rq) {
;         f32x4 v; v[0] = acc[nb][mb][4 * rq]; v[1] = acc[nb][mb][4 * rq + 1]; v[2] = acc[nb][mb][4 * rq + 2]; v[3] = acc[nb][mb][4 * rq + 3];
;         *(f32x4*)(wl + l32 * LROW + (8 * rq + 4 * hi) * 4) = v;
;       }
; #pragma unroll
;       for (int it = 0; it < 4; ++it) {
;         const f32x4 v = *(const f32x4*)(wl + (it * 8 + (lane >> 3)) * LROW + (lane & 7) * 16);
;         *(f32x4*)(out + o0 + (size_t)(32 * mb + 8 * it) * DM + 32 * nb) = v + bb[mb][nb][it];
.LBB0_271:
	s_ashr_i32 s15, s14, 31
	s_lshl_b64 s[4:5], s[14:15], 11
	s_mov_b64 s[64:65], s[80:81]
	s_lshl_b32 s86, s62, 7
	s_add_u32 s80, s82, 0xcc00000
	s_addc_u32 s81, s83, 0
	s_add_u32 s0, s82, 0xa00000
	s_addc_u32 s1, s83, 0
	s_ashr_i32 s87, s86, 31
	s_lshl_b64 s[2:3], s[86:87], 11
	v_mov_b32_e32 v2, v176
	s_barrier
	s_add_u32 s6, s80, s2
	s_addc_u32 s7, s81, s3
	v_readfirstlane_b32 s2, v2
	s_ashr_i32 s2, s2, 6
	v_bfe_u32 v0, v2, 3, 3
	v_lshl_or_b32 v0, s2, 3, v0
	v_lshrrev_b32_e32 v3, 1, v0
	v_xor_b32_e32 v2, v3, v2
	v_ashrrev_i32_e32 v1, 31, v0
	v_lshlrev_b32_e32 v2, 4, v2
	v_and_b32_e32 v120, 0x70, v2
	v_lshlrev_b64 v[0:1], 11, v[0:1]
	s_lshl_b32 s2, s2, 10
	v_or_b32_e32 v2, v0, v120
	v_mov_b32_e32 v3, v1
	s_add_i32 s2, s2, 0
	v_lshl_add_u64 v[4:5], s[6:7], 0, v[2:3]
	v_lshl_add_u64 v[6:7], v[2:3], 0, s[20:21]
	s_mov_b32 m0, s2
	v_writelane_b32 v231, s6, 13
	global_load_lds_dwordx4 v[4:5], off
	s_nop 0
	v_lshl_add_u64 v[8:9], s[6:7], 0, v[6:7]
	s_add_i32 m0, s2, 0x2000
	v_lshl_add_u64 v[2:3], s[0:1], 0, v[2:3]
	v_lshl_add_u64 v[0:1], s[0:1], 0, v[0:1]
	global_load_lds_dwordx4 v[8:9], off
	s_add_i32 m0, s2, 0x4000
	v_lshl_add_u64 v[6:7], s[0:1], 0, v[6:7]
	v_lshl_add_u64 v[0:1], v[0:1], 0, v[120:121]
	global_load_lds_dwordx4 v[2:3], off
	s_add_i32 m0, s2, 0x6000
	v_lshl_add_u64 v[10:11], v[0:1], 0, s[22:23]
	global_load_lds_dwordx4 v[6:7], off
	s_add_i32 m0, s2, 0x8000
	v_lshl_add_u64 v[12:13], v[0:1], 0, s[24:25]
	global_load_lds_dwordx4 v[10:11], off
	s_add_i32 m0, s2, 0xa000
	v_lshl_add_u64 v[4:5], v[4:5], 0, s[96:97]
	global_load_lds_dwordx4 v[12:13], off
	s_add_i32 m0, s2, 0xc000
	v_lshl_add_u64 v[2:3], v[2:3], 0, s[96:97]
	global_load_lds_dwordx4 v[4:5], off
	v_lshl_add_u64 v[4:5], v[8:9], 0, s[96:97]
	s_add_i32 m0, s2, 0xe000
	v_writelane_b32 v231, s7, 14
	global_load_lds_dwordx4 v[4:5], off
	s_add_i32 m0, s2, 0x10000
	s_mov_b32 s9, s27
	global_load_lds_dwordx4 v[2:3], off
	v_lshl_add_u64 v[2:3], v[6:7], 0, s[96:97]
	s_add_i32 m0, s2, 0x12000
	s_nop 0
	global_load_lds_dwordx4 v[2:3], off
	v_lshl_add_u64 v[2:3], v[0:1], 0, s[34:35]
	s_add_i32 m0, s2, 0x14000
	v_lshl_add_u64 v[0:1], v[0:1], 0, s[36:37]
	global_load_lds_dwordx4 v[2:3], off
	s_add_i32 m0, s2, 0x16000
	s_add_u32 s2, s82, s4
	global_load_lds_dwordx4 v[0:1], off
	s_addc_u32 s3, s83, s5
	s_add_u32 s2, s2, 0xcc00100
	s_addc_u32 s3, s3, 0
	v_writelane_b32 v231, s2, 15
	s_mov_b64 s[4:5], s[0:1]
	s_nop 0
	v_writelane_b32 v231, s3, 16
	s_mov_b32 s2, s27
	s_waitcnt vmcnt(12)
	s_branch .LBB0_273
.LBB0_272:
	v_mov_b32_e32 v86, v176
	s_lshl_b32 s26, s2, 8
	v_ashrrev_i32_e32 v66, 1, v86
	v_and_b32_e32 v64, 64, v86
	v_bfe_u32 v87, v86, 3, 3
	v_and_b32_e32 v66, 0xffffffc0, v66
	v_or3_b32 v64, v64, s86, v87
	v_ashrrev_i32_e32 v67, 31, v66
	v_ashrrev_i32_e32 v65, 31, v64
	v_and_b32_e32 v90, 7, v86
	v_lshl_add_u64 v[66:67], v[66:67], 0, s[26:27]
	v_lshlrev_b64 v[64:65], 10, v[64:65]
	v_lshl_or_b32 v66, v90, 2, v66
	v_lshl_add_u64 v[64:65], v[66:67], 0, v[64:65]
	v_lshlrev_b64 v[96:97], 2, v[64:65]
	v_lshl_add_u64 v[100:101], s[52:53], 0, v[96:97]
	global_load_dwordx4 v[64:67], v[100:101], off
	global_load_dwordx4 v[80:83], v[100:101], off offset:128
	v_add_co_u32_e32 v84, vcc, s28, v100
	v_lshrrev_b32_e32 v91, 6, v86
	s_nop 0
	v_addc_co_u32_e32 v85, vcc, 0, v101, vcc
	global_load_dwordx4 v[68:71], v[84:85], off
	v_add_co_u32_e32 v88, vcc, s31, v100
	v_and_b32_e32 v92, 31, v86
	s_nop 0
	v_addc_co_u32_e32 v89, vcc, 0, v101, vcc
	global_load_dwordx4 v[72:75], v[88:89], off
	v_add_co_u32_e32 v98, vcc, s33, v100
	v_lshrrev_b32_e32 v86, 1, v86
	s_nop 0
	v_addc_co_u32_e32 v99, vcc, 0, v101, vcc
	global_load_dwordx4 v[76:79], v[98:99], off
	v_and_b32_e32 v93, 16, v86
	v_mul_u32_u24_e32 v94, 0x90, v87
	global_load_dwordx4 v[84:87], v[84:85], off offset:128
	s_add_i32 s2, s9, 0
	v_mul_lo_u32 v91, v91, s38
	v_mul_u32_u24_e32 v92, 0x90, v92
	v_add_u32_e32 v91, s2, v91
	v_add3_u32 v120, v91, v92, v93
	v_lshlrev_b32_e32 v90, 4, v90
	ds_write_b128 v120, v[48:51]
	ds_write_b128 v120, v[52:55] offset:32
	ds_write_b128 v120, v[56:59] offset:64
	ds_write_b128 v120, v[60:63] offset:96
	v_add3_u32 v122, v91, v90, v94
	global_load_dwordx4 v[88:91], v[88:89], off offset:128
	v_lshl_add_u64 v[116:117], s[64:65], 0, v[96:97]
	global_load_dwordx4 v[96:99], v[98:99], off offset:128
	v_add_co_u32_e32 v48, vcc, s39, v100
	ds_read_b128 v[92:95], v122
	s_nop 0
	v_addc_co_u32_e32 v49, vcc, 0, v101, vcc
	v_add_co_u32_e32 v50, vcc, s40, v100
	s_mov_b32 s9, s8
	s_nop 0
	v_addc_co_u32_e32 v51, vcc, 0, v101, vcc
	v_add_co_u32_e32 v52, vcc, s41, v100
	s_cmp_lg_u32 s3, 4
	s_nop 0
	v_addc_co_u32_e32 v53, vcc, 0, v101, vcc
	v_add_co_u32_e32 v118, vcc, s42, v100
	s_mov_b32 s2, s3
	s_nop 0
	v_addc_co_u32_e32 v119, vcc, 0, v101, vcc
	global_load_dwordx4 v[100:103], v[48:49], off
	global_load_dwordx4 v[60:63], v[48:49], off offset:128
	global_load_dwordx4 v[104:107], v[50:51], off
	global_load_dwordx4 v[56:59], v[50:51], off offset:128
	global_load_dwordx4 v[108:111], v[52:53], off
	s_nop 0
	global_load_dwordx4 v[52:55], v[52:53], off offset:128
	s_nop 0
	global_load_dwordx4 v[112:115], v[118:119], off
	global_load_dwordx4 v[48:51], v[118:119], off offset:128
	s_waitcnt vmcnt(0) lgkmcnt(0)
	v_pk_add_f32 v[66:67], v[66:67], v[94:95]
	v_pk_add_f32 v[64:65], v[64:65], v[92:93]
	flat_store_dwordx4 v[116:117], v[64:67]
	ds_read_b128 v[64:67], v122 offset:1152
	v_add_co_u32_e32 v92, vcc, s28, v116
	s_waitcnt lgkmcnt(0)
	v_pk_add_f32 v[66:67], v[70:71], v[66:67]
	v_addc_co_u32_e32 v93, vcc, 0, v117, vcc
	v_pk_add_f32 v[64:65], v[68:69], v[64:65]
	flat_store_dwordx4 v[92:93], v[64:67]
	ds_read_b128 v[64:67], v122 offset:2304
	v_add_co_u32_e32 v68, vcc, s31, v116
	s_waitcnt lgkmcnt(0)
; DEV void epi_resid_f32(const f32x16 (&acc)[2][2], const float* base, float* out, int m0, int n0, int stg) {
;     ...
;   for (int mb = 0; mb < 2; ++mb)
; #pragma unroll
;     for (int nb = 0; nb < 2; ++nb) {
; #pragma unroll
;       for (int rq = 0; rq < 4; ++rq) {
;         f32x4 v; v[0] = acc[nb][mb][4 * rq]; v[1] = acc[nb][mb][4 * rq + 1]; v[2] = acc[nb][mb][4 * rq + 2]; v[3] = acc[nb][mb][4 * rq + 3];
;         *(f32x4*)(wl + l32 * LROW + (8 * rq + 4 * hi) * 4) = v;
;       }
; #pragma unroll
;       for (int it = 0; it < 4; ++it) {
;         const f32x4 v = *(const f32x4*)(wl + (it * 8 + (lane >> 3)) * LROW + (lane & 7) * 16);
;         *(f32x4*)(out + o0 + (size_t)(32 * mb + 8 * it) * DM + 32 * nb) = v + bb[mb][nb][it];
;       }
;     }
	v_pk_add_f32 v[66:67], v[74:75], v[66:67]
	v_addc_co_u32_e32 v69, vcc, 0, v117, vcc
	v_pk_add_f32 v[64:65], v[72:73], v[64:65]
	flat_store_dwordx4 v[68:69], v[64:67]
	ds_read_b128 v[64:67], v122 offset:3456
	v_add_co_u32_e32 v70, vcc, s33, v116
	s_waitcnt lgkmcnt(0)
	v_pk_add_f32 v[66:67], v[78:79], v[66:67]
	v_addc_co_u32_e32 v71, vcc, 0, v117, vcc
	v_pk_add_f32 v[64:65], v[76:77], v[64:65]
	flat_store_dwordx4 v[70:71], v[64:67]
	ds_write_b128 v120, v[32:35]
	ds_write_b128 v120, v[36:39] offset:32
	ds_write_b128 v120, v[40:43] offset:64
	ds_write_b128 v120, v[44:47] offset:96
	ds_read_b128 v[32:35], v122
	s_waitcnt lgkmcnt(0)
	v_pk_add_f32 v[34:35], v[82:83], v[34:35]
	v_pk_add_f32 v[32:33], v[80:81], v[32:33]
	flat_store_dwordx4 v[116:117], v[32:35] offset:128
	ds_read_b128 v[32:35], v122 offset:1152
	s_waitcnt lgkmcnt(0)
	v_pk_add_f32 v[34:35], v[86:87], v[34:35]
	v_pk_add_f32 v[32:33], v[84:85], v[32:33]
	flat_store_dwordx4 v[92:93], v[32:35] offset:128
	ds_read_b128 v[32:35], v122 offset:2304
	s_waitcnt lgkmcnt(0)
	v_pk_add_f32 v[34:35], v[90:91], v[34:35]
	v_pk_add_f32 v[32:33], v[88:89], v[32:33]
	flat_store_dwordx4 v[68:69], v[32:35] offset:128
	ds_read_b128 v[32:35], v122 offset:3456
	s_waitcnt lgkmcnt(0)
	v_pk_add_f32 v[34:35], v[98:99], v[34:35]
	v_pk_add_f32 v[32:33], v[96:97], v[32:33]
	flat_store_dwordx4 v[70:71], v[32:35] offset:128
	ds_write_b128 v120, v[16:19]
	ds_write_b128 v120, v[20:23] offset:32
	ds_write_b128 v120, v[24:27] offset:64
	ds_write_b128 v120, v[28:31] offset:96
	ds_read_b128 v[16:19], v122
	v_add_co_u32_e32 v20, vcc, s39, v116
	s_waitcnt lgkmcnt(0)
	v_pk_add_f32 v[18:19], v[102:103], v[18:19]
	v_addc_co_u32_e32 v21, vcc, 0, v117, vcc
	v_pk_add_f32 v[16:17], v[100:101], v[16:17]
	flat_store_dwordx4 v[20:21], v[16:19]
	ds_read_b128 v[16:19], v122 offset:1152
	v_add_co_u32_e32 v22, vcc, s40, v116
	s_waitcnt lgkmcnt(0)
	v_pk_add_f32 v[18:19], v[106:107], v[18:19]
	v_addc_co_u32_e32 v23, vcc, 0, v117, vcc
	v_pk_add_f32 v[16:17], v[104:105], v[16:17]
	flat_store_dwordx4 v[22:23], v[16:19]
	ds_read_b128 v[16:19], v122 offset:2304
	v_add_co_u32_e32 v24, vcc, s41, v116
	s_waitcnt lgkmcnt(0)
	v_pk_add_f32 v[18:19], v[110:111], v[18:19]
	v_addc_co_u32_e32 v25, vcc, 0, v117, vcc
	v_pk_add_f32 v[16:17], v[108:109], v[16:17]
	flat_store_dwordx4 v[24:25], v[16:19]
	ds_read_b128 v[16:19], v122 offset:3456
	v_add_co_u32_e32 v26, vcc, s42, v116
	s_waitcnt lgkmcnt(0)
	v_pk_add_f32 v[18:19], v[114:115], v[18:19]
	v_addc_co_u32_e32 v27, vcc, 0, v117, vcc
	v_pk_add_f32 v[16:17], v[112:113], v[16:17]
	flat_store_dwordx4 v[26:27], v[16:19]
	ds_write_b128 v120, v[0:3]
	ds_write_b128 v120, v[4:7] offset:32
	ds_write_b128 v120, v[8:11] offset:64
	ds_write_b128 v120, v[12:15] offset:96
	ds_read_b128 v[0:3], v122
	s_waitcnt lgkmcnt(0)
	v_pk_add_f32 v[2:3], v[62:63], v[2:3]
	v_pk_add_f32 v[0:1], v[60:61], v[0:1]
	flat_store_dwordx4 v[20:21], v[0:3] offset:128
	ds_read_b128 v[0:3], v122 offset:1152
	s_waitcnt lgkmcnt(0)
	v_pk_add_f32 v[2:3], v[58:59], v[2:3]
	v_pk_add_f32 v[0:1], v[56:57], v[0:1]
	flat_store_dwordx4 v[22:23], v[0:3] offset:128
	ds_read_b128 v[0:3], v122 offset:2304
	s_waitcnt lgkmcnt(0)
	v_pk_add_f32 v[2:3], v[54:55], v[2:3]
	v_pk_add_f32 v[0:1], v[52:53], v[0:1]
	flat_store_dwordx4 v[24:25], v[0:3] offset:128
	ds_read_b128 v[0:3], v122 offset:3456
	s_waitcnt lgkmcnt(0)
	v_pk_add_f32 v[2:3], v[50:51], v[2:3]
	v_pk_add_f32 v[0:1], v[48:49], v[0:1]
	flat_store_dwordx4 v[26:27], v[0:3] offset:128
	s_cbranch_scc0 .LBB0_289
; DEV int tid_l() { int t = threadIdx.x; asm volatile("" : "+v"(t)); return t; }
; DEV int stage_next(int s) { return (s == 2 * GS_STAGE) ? 0 : s + GS_STAGE; }
; template <int WAIT0>
; DEV void gk_main(f32x16 (&acc)[2][2], const GTile& t, int s0) {
;   const int tid = tid_l(), lane = tid & 63, wid = __builtin_amdgcn_readfirstlane(tid >> 6), wm = wid & 1, wn = wid >> 1, l32 = lane & 31, hi = lane >> 5;
;   GK_SRC(t)
;   const int sw = (l32 >> 1) & 7;
;   int xk[4], wk[4];
; #pragma unroll
;   for (int ks = 0; ks < 4; ++ks) { const int ko = ((2 * ks + hi) ^ sw) << 4; xk[ks] = GS_A + (64 * wm + l32) * 128 + ko; wk[ks] = GS_B + (64 * wn + l32) * 128 + ko; }
;   const int nk = t.K >> 6;
;     ...
;   vm_wait_bar<WAIT0>();
;   int stc = s0, std_ = stage_next(stage_next(s0));
.LBB0_273:
	s_cmp_lg_u32 s2, 0
	s_cbranch_scc0 .LBB0_284
	s_bitcmp0_b32 s2, 0
	s_mov_b64 s[6:7], -1
	s_cbranch_scc1 .LBB0_278
	v_mov_b32_e32 v1, v176
	s_waitcnt vmcnt(22) lgkmcnt(0)
	s_barrier
	v_readfirstlane_b32 s3, v1
	s_ashr_i32 s6, s3, 6
	v_bfe_u32 v0, v1, 3, 3
	v_and_b32_e32 v2, 31, v1
	v_lshl_or_b32 v0, s6, 3, v0
	v_lshrrev_b32_e32 v3, 1, v0
	v_and_or_b32 v6, s3, 64, v2
	s_lshr_b32 s3, s3, 1
	v_xor_b32_e32 v3, v3, v1
	s_and_b32 s3, s3, 0x1ffffc0
	v_lshlrev_b32_e32 v3, 4, v3
	v_or_b32_e32 v2, s3, v2
	s_lshl_b32 s3, s6, 10
	v_and_b32_e32 v4, 0x70, v3
	v_bfe_u32 v3, v1, 5, 1
	v_lshrrev_b32_e32 v5, 1, v1
	v_bfe_u32 v1, v1, 1, 3
	s_add_i32 s10, s3, 0
	s_add_i32 s3, s9, 0xc000
	v_bitop3_b32 v5, v3, v5, 7 bitop3:0x78
	v_bitop3_b32 v7, v3, v1, 2 bitop3:0x36
	v_bitop3_b32 v8, v3, v1, 4 bitop3:0x36
	v_bitop3_b32 v1, v3, v1, 6 bitop3:0x36
	s_cmp_lg_u32 s9, 0x18000
	v_lshlrev_b32_e32 v2, 7, v2
	v_lshlrev_b32_e32 v5, 4, v5
	v_lshlrev_b32_e32 v7, 4, v7
	v_lshlrev_b32_e32 v8, 4, v8
	v_lshlrev_b32_e32 v1, 4, v1
	s_cselect_b32 s8, s3, 0
	s_add_i32 s3, s8, 0xc000
	v_or_b32_e32 v83, v2, v5
	v_or_b32_e32 v81, v2, v7
	v_or_b32_e32 v79, v2, v8
	v_or_b32_e32 v77, v2, v1
	v_add_u32_e32 v2, 0xc0, v0
	s_cmp_lg_u32 s8, 0x18000
	v_ashrrev_i32_e32 v3, 31, v2
	s_cselect_b32 s11, s3, 0
	s_add_u32 s6, s4, 0x100
	v_lshlrev_b64 v[2:3], 11, v[2:3]
	s_addc_u32 s7, s5, 0
	v_or_b32_e32 v2, v2, v4
	v_lshl_add_u64 v[64:65], s[6:7], 0, v[2:3]
	v_add_u32_e32 v2, 0x80, v0
	v_ashrrev_i32_e32 v3, 31, v2
	v_lshlrev_b64 v[2:3], 11, v[2:3]
	v_or_b32_e32 v2, v2, v4
	v_lshlrev_b32_e32 v6, 7, v6
	v_lshl_add_u64 v[66:67], s[6:7], 0, v[2:3]
	v_add_u32_e32 v2, 64, v0
	v_or_b32_e32 v76, v1, v6
	v_ashrrev_i32_e32 v3, 31, v2
	v_ashrrev_i32_e32 v1, 31, v0
	v_lshlrev_b64 v[2:3], 11, v[2:3]
	v_lshlrev_b64 v[0:1], 11, v[0:1]
	v_or_b32_e32 v2, v2, v4
	v_or_b32_e32 v0, v0, v4
	v_lshl_add_u64 v[68:69], s[6:7], 0, v[2:3]
	v_lshl_add_u64 v[70:71], s[6:7], 0, v[0:1]
	v_readlane_b32 s6, v231, 15
	v_readlane_b32 s7, v231, 16
	v_or_b32_e32 v82, v5, v6
	v_or_b32_e32 v80, v7, v6
	v_lshl_add_u64 v[74:75], s[6:7], 0, v[0:1]
	v_mov_b32_e32 v0, 0
	v_or_b32_e32 v78, v8, v6
	v_lshl_add_u64 v[72:73], s[6:7], 0, v[2:3]
	s_mov_b64 s[6:7], 0
	s_mov_b32 s3, s9
	v_mov_b32_e32 v1, v0
	v_mov_b32_e32 v2, v0
	v_mov_b32_e32 v3, v0
	v_mov_b32_e32 v4, v0
	v_mov_b32_e32 v5, v0
	v_mov_b32_e32 v6, v0
	v_mov_b32_e32 v7, v0
	v_mov_b32_e32 v8, v0
	v_mov_b32_e32 v9, v0
	v_mov_b32_e32 v10, v0
	v_mov_b32_e32 v11, v0
	v_mov_b32_e32 v12, v0
	v_mov_b32_e32 v13, v0
	v_mov_b32_e32 v14, v0
	v_mov_b32_e32 v15, v0
	v_mov_b32_e32 v32, v0
	v_mov_b32_e32 v33, v0
	v_mov_b32_e32 v34, v0
	v_mov_b32_e32 v35, v0
	v_mov_b32_e32 v36, v0
	v_mov_b32_e32 v37, v0
	v_mov_b32_e32 v38, v0
	v_mov_b32_e32 v39, v0
	v_mov_b32_e32 v40, v0
	v_mov_b32_e32 v41, v0
	v_mov_b32_e32 v42, v0
	v_mov_b32_e32 v43, v0
	v_mov_b32_e32 v44, v0
	v_mov_b32_e32 v45, v0
	v_mov_b32_e32 v46, v0
	v_mov_b32_e32 v47, v0
	v_mov_b32_e32 v16, v0
	v_mov_b32_e32 v17, v0
	v_mov_b32_e32 v18, v0
	v_mov_b32_e32 v19, v0
	v_mov_b32_e32 v20, v0
	v_mov_b32_e32 v21, v0
	v_mov_b32_e32 v22, v0
	v_mov_b32_e32 v23, v0
	v_mov_b32_e32 v24, v0
	v_mov_b32_e32 v25, v0
	v_mov_b32_e32 v26, v0
	v_mov_b32_e32 v27, v0
	v_mov_b32_e32 v28, v0
	v_mov_b32_e32 v29, v0
	v_mov_b32_e32 v30, v0
	v_mov_b32_e32 v31, v0
	v_mov_b32_e32 v48, v0
	v_mov_b32_e32 v49, v0
	v_mov_b32_e32 v50, v0
	v_mov_b32_e32 v51, v0
	v_mov_b32_e32 v52, v0
	v_mov_b32_e32 v53, v0
	v_mov_b32_e32 v54, v0
	v_mov_b32_e32 v55, v0
	v_mov_b32_e32 v56, v0
	v_mov_b32_e32 v57, v0
	v_mov_b32_e32 v58, v0
	v_mov_b32_e32 v59, v0
	v_mov_b32_e32 v60, v0
	v_mov_b32_e32 v61, v0
	v_mov_b32_e32 v62, v0
	v_mov_b32_e32 v63, v0
	s_add_i32 s99, s3, 0
	v_add_u32_e32 v252, s99, v82
	v_add_u32_e32 v253, s99, v83
	ds_read_b128 v[84:87], v252
	ds_read_b128 v[88:91], v252 offset:4096
	ds_read_b128 v[92:95], v253 offset:16384
	ds_read_b128 v[96:99], v253 offset:20480

; DEV int tid_l() { int t = threadIdx.x; asm volatile("" : "+v"(t)); return t; }
; DEV int stage_next(int s) { return (s == 2 * GS_STAGE) ? 0 : s + GS_STAGE; }
; template <int WAIT0>
; DEV void gk_main(f32x16 (&acc)[2][2], const GTile& t, int s0) {
;   const int tid = tid_l(), lane = tid & 63, wid = __builtin_amdgcn_readfirstlane(tid >> 6), wm = wid & 1, wn = wid >> 1, l32 = lane & 31, hi = lane >> 5;
;   GK_SRC(t)
;   const int sw = (l32 >> 1) & 7;
;   int xk[4], wk[4];
; #pragma unroll
;   for (int ks = 0; ks < 4; ++ks) { const int ko = ((2 * ks + hi) ^ sw) << 4; xk[ks] = GS_A + (64 * wm + l32) * 128 + ko; wk[ks] = GS_B + (64 * wn + l32) * 128 + ko; }
;   const int nk = t.K >> 6;
;     ...
;   vm_wait_bar<WAIT0>();
;   int stc = s0, std_ = stage_next(stage_next(s0));
.LBB0_278:
	s_and_b64 vcc, exec, s[6:7]
	s_cbranch_vccz .LBB0_282
	s_nop 9
	v_mov_b32_e32 v1, v176
	s_waitcnt vmcnt(22) lgkmcnt(0)
	s_barrier
	v_readfirstlane_b32 s3, v1
	s_ashr_i32 s6, s3, 6
	v_bfe_u32 v0, v1, 3, 3
	v_and_b32_e32 v2, 31, v1
	v_lshl_or_b32 v0, s6, 3, v0
	v_lshrrev_b32_e32 v3, 1, v0
	v_and_or_b32 v6, s3, 64, v2
	s_lshr_b32 s3, s3, 1
	v_xor_b32_e32 v3, v3, v1
	s_and_b32 s3, s3, 0x1ffffc0
	v_lshlrev_b32_e32 v3, 4, v3
	v_or_b32_e32 v2, s3, v2
	s_lshl_b32 s3, s6, 10
	v_and_b32_e32 v4, 0x70, v3
	v_bfe_u32 v3, v1, 5, 1
	v_lshrrev_b32_e32 v5, 1, v1
	v_bfe_u32 v1, v1, 1, 3
	s_add_i32 s10, s3, 0
	s_add_i32 s3, s9, 0xc000
	v_bitop3_b32 v5, v3, v5, 7 bitop3:0x78
	v_bitop3_b32 v7, v3, v1, 2 bitop3:0x36
	v_bitop3_b32 v8, v3, v1, 4 bitop3:0x36
	v_bitop3_b32 v1, v3, v1, 6 bitop3:0x36
	s_cmp_lg_u32 s9, 0x18000
	v_lshlrev_b32_e32 v2, 7, v2
	v_lshlrev_b32_e32 v5, 4, v5
	v_lshlrev_b32_e32 v7, 4, v7
	v_lshlrev_b32_e32 v8, 4, v8
	v_lshlrev_b32_e32 v1, 4, v1
	s_cselect_b32 s8, s3, 0
	s_add_i32 s3, s8, 0xc000
	v_or_b32_e32 v83, v2, v5
	v_or_b32_e32 v81, v2, v7
	v_or_b32_e32 v79, v2, v8
	v_or_b32_e32 v77, v2, v1
	v_add_u32_e32 v2, 0xc0, v0
	s_cmp_lg_u32 s8, 0x18000
	v_ashrrev_i32_e32 v3, 31, v2
	s_cselect_b32 s11, s3, 0
	s_add_u32 s6, s4, 0x100
	v_lshlrev_b64 v[2:3], 11, v[2:3]
	s_addc_u32 s7, s5, 0
	v_or_b32_e32 v2, v2, v4
	v_lshl_add_u64 v[64:65], s[6:7], 0, v[2:3]
	v_add_u32_e32 v2, 0x80, v0
	v_ashrrev_i32_e32 v3, 31, v2
	v_lshlrev_b64 v[2:3], 11, v[2:3]
	v_or_b32_e32 v2, v2, v4
	v_lshlrev_b32_e32 v6, 7, v6
	v_lshl_add_u64 v[66:67], s[6:7], 0, v[2:3]
	v_add_u32_e32 v2, 64, v0
	v_or_b32_e32 v76, v1, v6
	v_ashrrev_i32_e32 v3, 31, v2
	v_ashrrev_i32_e32 v1, 31, v0
	v_lshlrev_b64 v[2:3], 11, v[2:3]
	v_lshlrev_b64 v[0:1], 11, v[0:1]
	v_or_b32_e32 v2, v2, v4
	v_or_b32_e32 v0, v0, v4
	v_lshl_add_u64 v[68:69], s[6:7], 0, v[2:3]
	v_lshl_add_u64 v[70:71], s[6:7], 0, v[0:1]
	v_readlane_b32 s6, v231, 15
	v_readlane_b32 s7, v231, 16
	v_or_b32_e32 v82, v5, v6
	v_or_b32_e32 v80, v7, v6
	v_lshl_add_u64 v[74:75], s[6:7], 0, v[0:1]
	v_mov_b32_e32 v0, 0
	v_or_b32_e32 v78, v8, v6
	v_lshl_add_u64 v[72:73], s[6:7], 0, v[2:3]
	s_mov_b64 s[6:7], 0
	s_mov_b32 s3, s9
	v_mov_b32_e32 v1, v0
	v_mov_b32_e32 v2, v0
	v_mov_b32_e32 v3, v0
	v_mov_b32_e32 v4, v0
	v_mov_b32_e32 v5, v0
	v_mov_b32_e32 v6, v0
	v_mov_b32_e32 v7, v0
	v_mov_b32_e32 v8, v0
	v_mov_b32_e32 v9, v0
	v_mov_b32_e32 v10, v0
	v_mov_b32_e32 v11, v0
	v_mov_b32_e32 v12, v0
	v_mov_b32_e32 v13, v0
	v_mov_b32_e32 v14, v0
	v_mov_b32_e32 v15, v0
	v_mov_b32_e32 v32, v0
	v_mov_b32_e32 v33, v0
	v_mov_b32_e32 v34, v0
	v_mov_b32_e32 v35, v0
	v_mov_b32_e32 v36, v0
	v_mov_b32_e32 v37, v0
	v_mov_b32_e32 v38, v0
	v_mov_b32_e32 v39, v0
	v_mov_b32_e32 v40, v0
	v_mov_b32_e32 v41, v0
	v_mov_b32_e32 v42, v0
	v_mov_b32_e32 v43, v0
	v_mov_b32_e32 v44, v0
	v_mov_b32_e32 v45, v0
	v_mov_b32_e32 v46, v0
	v_mov_b32_e32 v47, v0
	v_mov_b32_e32 v16, v0
	v_mov_b32_e32 v17, v0
	v_mov_b32_e32 v18, v0
	v_mov_b32_e32 v19, v0
	v_mov_b32_e32 v20, v0
	v_mov_b32_e32 v21, v0
	v_mov_b32_e32 v22, v0
	v_mov_b32_e32 v23, v0
	v_mov_b32_e32 v24, v0
	v_mov_b32_e32 v25, v0
	v_mov_b32_e32 v26, v0
	v_mov_b32_e32 v27, v0
	v_mov_b32_e32 v28, v0
	v_mov_b32_e32 v29, v0
	v_mov_b32_e32 v30, v0
	v_mov_b32_e32 v31, v0
	v_mov_b32_e32 v48, v0
	v_mov_b32_e32 v49, v0
	v_mov_b32_e32 v50, v0
	v_mov_b32_e32 v51, v0
	v_mov_b32_e32 v52, v0
	v_mov_b32_e32 v53, v0
	v_mov_b32_e32 v54, v0
	v_mov_b32_e32 v55, v0
	v_mov_b32_e32 v56, v0
	v_mov_b32_e32 v57, v0
	v_mov_b32_e32 v58, v0
	v_mov_b32_e32 v59, v0
	v_mov_b32_e32 v60, v0
	v_mov_b32_e32 v61, v0
	v_mov_b32_e32 v62, v0
	v_mov_b32_e32 v63, v0
	s_add_i32 s99, s3, 0
	v_add_u32_e32 v252, s99, v82
	v_add_u32_e32 v253, s99, v83
	ds_read_b128 v[84:87], v252
	ds_read_b128 v[88:91], v252 offset:4096
	ds_read_b128 v[92:95], v253 offset:16384
	ds_read_b128 v[96:99], v253 offset:20480
